# hoist EpiBf16S ssq row-stat loads from epilogue to unit-loop header (in-proj, MLP-up), drop epilogue vmcnt(0)
# speedup vs baseline: 1.0003x; 1.0003x over previous
; #define PG8_STAGE(bufoff, gbase, voff) do { _Pragma("unroll") for (int _i = 0; _i < 2; ++_i) \
;         __builtin_amdgcn_global_load_lds((const unsigned*)((const char*)(gbase) + (voff)[_i]), (PG8_LAS unsigned*)(lds + (bufoff) + ldsw + _i * 8192), 16, 0, 0); } while (0)
; #define PG8_WAIT_V(n) asm volatile("s_waitcnt vmcnt(" #n ")" ::: "memory")
; template <class Epi, class Sched, bool ALIGN_EPI = false, bool SP2 = false>
; __device__ __forceinline__ void gemm_phase(PG8_LAS unsigned char* lds, const Gemm g, const Sched& S, const Epi& E) {
;     int tid_ = threadIdx.x; asm volatile("" : "+v"(tid_));
;     const int tid = tid_, wid = __builtin_amdgcn_readfirstlane(tid >> 6), lane = tid & 63, wr = wid >> 2, wc = wid & 3, fr = lane & 15, fq = lane >> 4;
;     const int K = g.K, nt = K / BK;
;     unsigned voffA[2], voffB[2];
; #pragma unroll
;     for (int i = 0; i < 2; ++i) { int R, C; stage_rc(tid * 16 + i * 8192, R, C); const int Rb = Epi::PERM ? ((R & ~31) + perm32(R & 31)) : R;
;         voffA[i] = (unsigned)(R * K + C) * 2u; voffB[i] = (unsigned)(Rb * K + C) * 2u; }
;     const size_t kstep = (size_t)(BK * 2);
;     const size_t hstep = (size_t)HALF * K * 2;
;     const size_t tstep = 2 * hstep;
;     const unsigned ldsw = (unsigned)wid * 1024u;
;     const int aoff = lds_byte(wr * 64 + fr, fq * 8), boff = lds_byte(wc * 32 + fr, fq * 8);
;     ...
;     Unit cur, nxt; int ui = 0;
;     if (!S.next(0, cur)) return;
;     f32x4 acc[2][2][4][2];
; #pragma unroll
;     for (int a = 0; a < 2; ++a)
; #pragma unroll
;         for (int b = 0; b < 2; ++b)
; #pragma unroll
;             for (int m = 0; m < 4; ++m)
; #pragma unroll
;                 for (int n = 0; n < 2; ++n) acc[a][b][m][n] = (f32x4){0.f, 0.f, 0.f, 0.f};
;     bf16x8 At[4][2], B0[2][2], B1[2][2];
;     const char* cA = (const char*)g.A + (size_t)cur.pm * tstep; const char* cB = (const char*)g.Bt + (size_t)cur.pn * tstep;
;     S.a_ready(cur);
;     if constexpr (SP2) {
;         PG8_STAGE(PG8_SB(0, 0), cB, voffB); PG8_STAGE(PG8_SB(0, 1), cB + hstep, voffB); PG8_STAGE(PG8_SA(0, 0), cA, voffA); PG8_STAGE(PG8_SA(0, 1), cA + hstep, voffA);
;         if (wr == 1) PG8_BAR;
;         PG8_WAIT_V(2); PG8_BAR;
;         PG8_STAGE(PG8_SB(1, 0), cB + kstep, voffB); PG8_STAGE(PG8_SA(1, 0), cA + kstep, voffA); PG8_STAGE(PG8_SB(1, 1), cB + hstep + kstep, voffB);
;         PG8_WAIT_V(6); PG8_BAR;
.LBB0_256:
	s_or_b64 exec, exec, s[16:17]
	v_readlane_b32 s4, v245, 36
	s_mov_b64 s[16:17], s[72:73]
	s_waitcnt vmcnt(5)
	v_mov_b32_e32 v10, v202
	v_readlane_b32 s5, v245, 37
	s_waitcnt lgkmcnt(0)
	s_barrier
	s_andn2_b64 vcc, exec, s[4:5]
	v_readfirstlane_b32 s2, v10
	s_cbranch_vccnz .LBB0_272
	v_lshlrev_b32_e32 v0, 4, v10
	v_add_u32_e32 v2, 0x2000, v0
	v_ashrrev_i32_e32 v3, 31, v2
	v_lshrrev_b32_e32 v3, 22, v3
	v_add_u32_e32 v3, v2, v3
	v_ashrrev_i32_e32 v11, 10, v3
	v_mul_i32_i24_e32 v3, 0x400, v11
	v_sub_u32_e32 v2, v2, v3
	v_lshrrev_b32_e32 v3, 4, v2
	v_bitop3_b32 v2, v3, v2, 32 bitop3:0x6c
	v_ashrrev_i32_e32 v3, 31, v2
	v_lshrrev_b32_e32 v3, 26, v3
	v_add_u32_e32 v3, v2, v3
	v_lshlrev_b32_e32 v4, 3, v11
	v_ashrrev_i32_e32 v12, 6, v3
	v_and_b32_e32 v4, -16, v4
	v_add_u32_e32 v4, v12, v4
	v_and_b32_e32 v5, 3, v12
	s_mov_b32 s7, 0xfffe0
	v_lshrrev_b32_e32 v6, 2, v4
	v_lshlrev_b32_e32 v7, 1, v4
	v_and_b32_e32 v3, 0xc0, v3
	v_and_or_b32 v5, v4, s7, v5
	v_and_b32_e32 v6, 4, v6
	v_and_b32_e32 v7, 24, v7
	v_sub_u32_e32 v2, v2, v3
	v_or3_b32 v5, v5, v6, v7
	v_lshlrev_b32_e32 v6, 5, v11
	v_ashrrev_i16_sdwa v2, v206, sext(v2) dst_sel:DWORD dst_unused:UNUSED_PAD src0_sel:DWORD src1_sel:BYTE_0
	v_and_b32_e32 v6, 32, v6
	v_bfe_i32 v13, v2, 0, 16
	v_add_lshl_u32 v2, v6, v13, 1
	v_lshl_add_u32 v142, v5, 12, v2
	v_lshl_add_u32 v144, v4, 12, v2
	v_bfe_i32 v2, v10, 27, 1
	v_lshrrev_b32_e32 v2, 22, v2
	v_add_u32_e32 v2, v0, v2
	v_and_b32_e32 v2, 0xfffffc00, v2
	v_sub_u32_e32 v0, v0, v2
	s_load_dwordx2 s[24:25], s[16:17], 0x80
	v_lshrrev_b32_e32 v2, 4, v0
	v_ashrrev_i32_e32 v3, 31, v10
	v_bitop3_b32 v0, v2, v0, 32 bitop3:0x6c
	v_lshrrev_b32_e32 v3, 26, v3
	v_ashrrev_i32_e32 v2, 31, v0
	v_add_u32_e32 v3, v10, v3
	v_lshrrev_b32_e32 v2, 26, v2
	s_waitcnt vmcnt(4)
	v_ashrrev_i32_e32 v15, 6, v3
	v_add_u32_e32 v2, v0, v2
	v_lshlrev_b32_e32 v3, 3, v15
	s_waitcnt lgkmcnt(0)
	s_add_u32 s52, s24, 0x6400000
	v_ashrrev_i32_e32 v14, 6, v2
	v_and_b32_e32 v3, -16, v3
	s_addc_u32 s53, s25, 0
	v_add_u32_e32 v3, v14, v3
	s_add_u32 s54, s24, 0x400000
	v_and_b32_e32 v4, 3, v14
	v_lshrrev_b32_e32 v5, 2, v3
	v_lshlrev_b32_e32 v6, 1, v3
	v_and_b32_e32 v2, 0xc0, v2
	s_addc_u32 s55, s25, 0
	s_ashr_i32 s5, s2, 6
	v_and_or_b32 v4, v3, s7, v4
	v_and_b32_e32 v5, 4, v5
	v_and_b32_e32 v6, 24, v6
	v_sub_u32_e32 v0, v0, v2
	s_ashr_i32 s4, s2, 8
	s_lshl_b32 s56, s5, 10
	v_or3_b32 v4, v4, v5, v6
	v_lshlrev_b32_e32 v5, 5, v15
	v_ashrrev_i16_sdwa v0, v206, sext(v0) dst_sel:DWORD dst_unused:UNUSED_PAD src0_sel:DWORD src1_sel:BYTE_0
	v_readlane_b32 s8, v245, 48
	v_and_b32_e32 v5, 32, v5
	v_bfe_i32 v16, v0, 0, 16
	v_readlane_b32 s9, v245, 49
	s_add_u32 s18, s54, s8
	v_add_lshl_u32 v2, v5, v16, 1
	s_addc_u32 s19, s55, s9
	s_add_i32 s57, s56, 0
	v_lshl_add_u32 v0, v4, 12, v2
	s_add_i32 m0, s57, 0x10000
	v_lshl_add_u32 v146, v3, 12, v2
	global_load_lds_dwordx4 v0, s[18:19]
	s_add_i32 m0, s57, 0x12000
	s_add_u32 s8, s18, 0x80000
	global_load_lds_dwordx4 v142, s[18:19]
	s_addc_u32 s9, s19, 0
	s_add_i32 m0, s57, 0x14000
	v_mov_b32_e32 v143, v1
	global_load_lds_dwordx4 v0, s[8:9]
	s_add_i32 m0, s57, 0x16000
	v_mov_b32_e32 v147, v1
	global_load_lds_dwordx4 v142, s[8:9]
	v_readlane_b32 s8, v245, 52
	v_readlane_b32 s9, v245, 53
	s_add_u32 s16, s52, s8
	s_addc_u32 s17, s53, s9
	s_add_i32 s58, s57, 0x2000
	s_mov_b32 m0, s57
	s_add_u32 s8, s16, 0x80000
	global_load_lds_dwordx4 v146, s[16:17]
	s_mov_b32 m0, s58
	s_addc_u32 s9, s17, 0
	s_add_i32 s59, s57, 0x4000
	global_load_lds_dwordx4 v144, s[16:17]
	s_mov_b32 m0, s59
	s_add_i32 s60, s57, 0x6000
	global_load_lds_dwordx4 v146, s[8:9]
	s_mov_b32 m0, s60
	v_mov_b32_e32 v145, v1
	global_load_lds_dwordx4 v144, s[8:9]
	s_cmp_eq_u32 s4, 1
	v_lshl_add_u64 v[8:9], s[18:19], 0, v[0:1]
	v_lshl_add_u64 v[6:7], s[18:19], 0, v[142:143]
	v_lshl_add_u64 v[2:3], s[16:17], 0, v[146:147]
	s_cselect_b64 s[42:43], -1, 0
	s_cmp_lg_u32 s4, 1
	v_lshl_add_u64 v[4:5], s[16:17], 0, v[144:145]
	s_cbranch_scc1 .LBB0_259
	s_barrier

;     __host__ __device__ bool next(int i, Unit& u) const {
;         const long L = (long)i * G + c; if (L >= nwg) return false;
;         int wgid = (int)L; { const int q = nwg / NXCD, r = nwg % NXCD, xcd = wgid % NXCD, off = wgid / NXCD; wgid = (xcd < r ? xcd * (q + 1) : r * (q + 1) + (xcd - r) * q) + off; }
;         const int nig = wgm * nN, gid = wgid / nig, fm = gid * wgm, gsz = (nM - fm) < wgm ? (nM - fm) : wgm;
;         u.pm = fm + ((wgid % nig) % gsz); u.pn = (wgid % nig) / gsz; return true;
; template <class Epi, class Sched, bool ALIGN_EPI = false, bool SP2 = false>
; __device__ __forceinline__ void gemm_phase(PG8_LAS unsigned char* lds, const Gemm g, const Sched& S, const Epi& E) {
;     ...
;         const bool has_next = S.next(ui + 1, nxt);
.LBB0_262:
	v_lshl_add_u32 v200, s4, 8, v156
	v_ashrrev_i32_e32 v201, 31, v200
	v_lshl_add_u64 v[200:201], v[200:201], 2, s[46:47]
	global_load_dword v247, v[200:201], off
	global_load_dword v248, v[200:201], off offset:64
	global_load_dword v249, v[200:201], off offset:128
	global_load_dword v250, v[200:201], off offset:192
	global_load_dword v251, v[200:201], off offset:512
	global_load_dword v252, v[200:201], off offset:576
	global_load_dword v253, v[200:201], off offset:640
	global_load_dword v254, v[200:201], off offset:704
	s_add_i32 s14, s14, 1
	s_mul_i32 s5, s14, s33
	s_mul_hi_u32 s7, s14, s70
	s_add_i32 s7, s7, s5
	s_mul_i32 s5, s14, s70
	s_add_u32 s28, s5, s6
	s_addc_u32 s29, s7, s97
	v_cmp_gt_i64_e32 vcc, s[28:29], v[132:133]
	v_cmp_lt_i64_e64 s[40:41], s[28:29], v[130:131]
	s_cbranch_vccnz .LBB0_264
	s_ashr_i32 s5, s28, 31
	s_lshr_b32 s5, s5, 29
	s_add_i32 s5, s28, s5
	s_ashr_i32 s7, s5, 3
	s_and_b32 s5, s5, -8
	s_sub_i32 s5, s28, s5
	s_cmp_lt_i32 s5, 0
	s_movk_i32 s8, 0xc1
	s_cselect_b32 s8, s8, 0xc0
	s_mul_i32 s5, s5, s8
	s_add_i32 s5, s5, s7
	s_mul_hi_i32 s7, s5, 0x2aaaaaab
	s_lshr_b32 s8, s7, 31
	s_ashr_i32 s7, s7, 5
	s_add_i32 s7, s7, s8
	s_lshl_b32 s8, s7, 3
	s_sub_i32 s9, 64, s8
	s_min_i32 s9, s9, 8
	s_abs_i32 s10, s9
	v_cvt_f32_u32_e32 v2, s10
	s_sub_i32 s15, 0, s10
	s_mulk_i32 s7, 0xc0
	s_sub_i32 s5, s5, s7
	v_rcp_iflag_f32_e32 v2, v2
	s_abs_i32 s7, s5
	s_xor_b32 s11, s5, s9
	s_ashr_i32 s11, s11, 31
	v_mul_f32_e32 v2, 0x4f7ffffe, v2
	v_cvt_u32_f32_e32 v2, v2
	s_nop 0
	v_readfirstlane_b32 s22, v2
	s_mul_i32 s15, s15, s22
	s_mul_hi_u32 s15, s22, s15
	s_add_i32 s22, s22, s15
	s_mul_hi_u32 s15, s7, s22
	s_mul_i32 s22, s15, s10
	s_sub_i32 s7, s7, s22
	s_add_i32 s23, s15, 1
	s_sub_i32 s22, s7, s10
	s_cmp_ge_u32 s7, s10
	s_cselect_b32 s15, s23, s15
	s_cselect_b32 s7, s22, s7
	s_add_i32 s22, s15, 1
	s_cmp_ge_u32 s7, s10
	s_cselect_b32 s7, s22, s15
	s_xor_b32 s7, s7, s11
	s_sub_i32 s26, s7, s11
	s_mul_i32 s7, s26, s9
	s_sub_i32 s5, s5, s7
	s_add_i32 s34, s8, s5

; __device__ __forceinline__ unsigned cvt_pk_bf16(float lo, float hi) { unsigned r; asm volatile("v_cvt_pk_bf16_f32 %0, %1, %2" : "=v"(r) : "v"(lo), "v"(hi)); return r; }
;     __device__ __forceinline__ void operator()(const f32x4 (&acc)[2][2][4][2], const Unit& u, int wr, int wc, int fr, int fq) const {
;     ...
;             for (int m = 0; m < 4; ++m) sv[ai][m] = ssq[row0 + ai * HALF + m * 16];
;         asm volatile("" ::: "memory");
; #pragma unroll
;         for (int ai = 0; ai < 2; ++ai)
; #pragma unroll
;             for (int m = 0; m < 4; ++m) {
;                 const int row = row0 + ai * HALF + m * 16;
;                 const float rs = __builtin_amdgcn_rsqf(sv[ai][m] * (1.0f / 2048.0f) + 1e-6f);
;                 bf16_t* rowp = O + (size_t)row * ldc + col0;
; #pragma unroll
;                 for (int bj = 0; bj < 2; ++bj) {
;                     f32x4 v0 = acc[ai][bj][m][0] * rs, v1 = acc[ai][bj][m][1] * rs;
;                     if (ACT == 1) {
; #pragma unroll
;                         for (int e = 0; e < 4; ++e) { float a = fmaxf(v0[e], 0.f); v0[e] = a * a; float b = fmaxf(v1[e], 0.f); v1[e] = b * b; }
;                     }
;                     u32x4 w; w.x = cvt_pk_bf16(v0[0], v0[1]); w.y = cvt_pk_bf16(v0[2], v0[3]); w.z = cvt_pk_bf16(v1[0], v1[1]); w.w = cvt_pk_bf16(v1[2], v1[3]);
;                     *(u32x4*)(rowp + bj * HALF) = w;
.LBB0_268:
	v_lshl_add_u32 v154, s4, 8, v156
	v_ashrrev_i32_e32 v155, 31, v154
	v_lshl_add_u64 v[152:153], v[154:155], 2, s[46:47]
	v_lshl_or_b32 v170, s2, 8, v158
	v_ashrrev_i32_e32 v171, 31, v170
	v_or_b32_e32 v169, 16, v154
	v_or_b32_e32 v176, 32, v154
	v_or_b32_e32 v168, 48, v154
	v_add_u32_e32 v166, 0x80, v154
	v_add_u32_e32 v164, 0x90, v154
	v_add_u32_e32 v162, 0xa0, v154
	v_add_u32_e32 v160, 0xb0, v154
	s_mov_b64 s[16:17], -1
	s_andn2_b64 vcc, exec, s[40:41]
	v_fmamk_f32 v152, v247, 0x3a000000, v207
	v_rsq_f32_e32 v172, v152
	v_mov_b64_e32 v[152:153], s[44:45]
	v_mad_i64_i32 v[174:175], s[4:5], v154, s1, v[152:153]
	v_lshlrev_b64 v[154:155], 1, v[170:171]
	v_lshl_add_u64 v[170:171], v[174:175], 0, v[154:155]
	v_pk_mul_f32 v[128:129], v[128:129], v[172:173] op_sel_hi:[1,0]
	v_pk_mul_f32 v[126:127], v[126:127], v[172:173] op_sel_hi:[1,0]
	v_pk_mul_f32 v[174:175], v[124:125], v[172:173] op_sel_hi:[1,0]
	v_pk_mul_f32 v[124:125], v[122:123], v[172:173] op_sel_hi:[1,0]
	v_cvt_pk_bf16_f32 v122, v126, v127
	v_cvt_pk_bf16_f32 v123, v128, v129
	v_pk_mul_f32 v[118:119], v[118:119], v[172:173] op_sel_hi:[1,0]
	v_cvt_pk_bf16_f32 v124, v124, v125
	v_cvt_pk_bf16_f32 v125, v174, v175
	global_store_dwordx4 v[170:171], v[122:125], off
	v_pk_mul_f32 v[120:121], v[120:121], v[172:173] op_sel_hi:[1,0]
	s_nop 0
	v_pk_mul_f32 v[122:123], v[116:117], v[172:173] op_sel_hi:[1,0]
	v_pk_mul_f32 v[116:117], v[114:115], v[172:173] op_sel_hi:[1,0]
	v_cvt_pk_bf16_f32 v114, v118, v119
	v_cvt_pk_bf16_f32 v115, v120, v121
	s_nop 0
	v_cvt_pk_bf16_f32 v116, v116, v117
	v_cvt_pk_bf16_f32 v117, v122, v123
	global_store_dwordx4 v[170:171], v[114:117], off offset:256
	s_nop 1
	v_fmamk_f32 v114, v248, 0x3a000000, v207
	v_rsq_f32_e32 v114, v114
	v_mad_i64_i32 v[116:117], s[4:5], v169, s1, v[152:153]
	v_lshl_add_u64 v[116:117], v[116:117], 0, v[154:155]
	v_pk_mul_f32 v[112:113], v[112:113], v[114:115] op_sel_hi:[1,0]
	v_pk_mul_f32 v[110:111], v[110:111], v[114:115] op_sel_hi:[1,0]
	v_pk_mul_f32 v[118:119], v[108:109], v[114:115] op_sel_hi:[1,0]
	v_pk_mul_f32 v[108:109], v[106:107], v[114:115] op_sel_hi:[1,0]
	v_cvt_pk_bf16_f32 v106, v110, v111
	v_cvt_pk_bf16_f32 v107, v112, v113
	v_pk_mul_f32 v[102:103], v[102:103], v[114:115] op_sel_hi:[1,0]
	v_cvt_pk_bf16_f32 v108, v108, v109
	v_cvt_pk_bf16_f32 v109, v118, v119
	global_store_dwordx4 v[116:117], v[106:109], off
	v_pk_mul_f32 v[104:105], v[104:105], v[114:115] op_sel_hi:[1,0]
	s_nop 0
	v_pk_mul_f32 v[106:107], v[100:101], v[114:115] op_sel_hi:[1,0]
	v_pk_mul_f32 v[100:101], v[98:99], v[114:115] op_sel_hi:[1,0]
	v_cvt_pk_bf16_f32 v98, v102, v103
	v_cvt_pk_bf16_f32 v99, v104, v105
	s_nop 0
	v_cvt_pk_bf16_f32 v100, v100, v101
	v_cvt_pk_bf16_f32 v101, v106, v107
	global_store_dwordx4 v[116:117], v[98:101], off offset:256
	s_nop 1
	v_fmamk_f32 v98, v249, 0x3a000000, v207
	v_rsq_f32_e32 v98, v98
	v_mad_i64_i32 v[100:101], s[4:5], v176, s1, v[152:153]
	v_lshl_add_u64 v[100:101], v[100:101], 0, v[154:155]
	v_pk_mul_f32 v[96:97], v[96:97], v[98:99] op_sel_hi:[1,0]
	v_pk_mul_f32 v[94:95], v[94:95], v[98:99] op_sel_hi:[1,0]
	v_pk_mul_f32 v[102:103], v[92:93], v[98:99] op_sel_hi:[1,0]
	v_pk_mul_f32 v[92:93], v[90:91], v[98:99] op_sel_hi:[1,0]
	v_cvt_pk_bf16_f32 v90, v94, v95
	v_cvt_pk_bf16_f32 v91, v96, v97
	v_pk_mul_f32 v[86:87], v[86:87], v[98:99] op_sel_hi:[1,0]
	v_cvt_pk_bf16_f32 v92, v92, v93
	v_cvt_pk_bf16_f32 v93, v102, v103
	global_store_dwordx4 v[100:101], v[90:93], off
	v_pk_mul_f32 v[88:89], v[88:89], v[98:99] op_sel_hi:[1,0]
	s_nop 0
	v_pk_mul_f32 v[90:91], v[84:85], v[98:99] op_sel_hi:[1,0]
	v_pk_mul_f32 v[84:85], v[82:83], v[98:99] op_sel_hi:[1,0]
	v_cvt_pk_bf16_f32 v82, v86, v87
	v_cvt_pk_bf16_f32 v83, v88, v89
	s_nop 0
	v_cvt_pk_bf16_f32 v84, v84, v85
	v_cvt_pk_bf16_f32 v85, v90, v91
	global_store_dwordx4 v[100:101], v[82:85], off offset:256
	s_nop 1
	v_fmamk_f32 v82, v250, 0x3a000000, v207
	v_rsq_f32_e32 v82, v82
	v_mad_i64_i32 v[84:85], s[4:5], v168, s1, v[152:153]
	v_lshl_add_u64 v[84:85], v[84:85], 0, v[154:155]
	v_pk_mul_f32 v[80:81], v[80:81], v[82:83] op_sel_hi:[1,0]
	v_pk_mul_f32 v[78:79], v[78:79], v[82:83] op_sel_hi:[1,0]
	v_pk_mul_f32 v[86:87], v[76:77], v[82:83] op_sel_hi:[1,0]
	v_pk_mul_f32 v[76:77], v[74:75], v[82:83] op_sel_hi:[1,0]
	v_cvt_pk_bf16_f32 v74, v78, v79
	v_cvt_pk_bf16_f32 v75, v80, v81
	v_pk_mul_f32 v[70:71], v[70:71], v[82:83] op_sel_hi:[1,0]
	v_cvt_pk_bf16_f32 v76, v76, v77
	v_cvt_pk_bf16_f32 v77, v86, v87
	global_store_dwordx4 v[84:85], v[74:77], off
	v_pk_mul_f32 v[72:73], v[72:73], v[82:83] op_sel_hi:[1,0]
	s_nop 0
; __device__ __forceinline__ unsigned cvt_pk_bf16(float lo, float hi) { unsigned r; asm volatile("v_cvt_pk_bf16_f32 %0, %1, %2" : "=v"(r) : "v"(lo), "v"(hi)); return r; }
; #define PG8_BAR __builtin_amdgcn_s_barrier()
;     __device__ __forceinline__ void operator()(const f32x4 (&acc)[2][2][4][2], const Unit& u, int wr, int wc, int fr, int fq) const {
;     ...
;         for (int ai = 0; ai < 2; ++ai)
; #pragma unroll
;             for (int m = 0; m < 4; ++m) {
;                 const int row = row0 + ai * HALF + m * 16;
;                 const float rs = __builtin_amdgcn_rsqf(sv[ai][m] * (1.0f / 2048.0f) + 1e-6f);
;                 bf16_t* rowp = O + (size_t)row * ldc + col0;
; #pragma unroll
;                 for (int bj = 0; bj < 2; ++bj) {
;                     f32x4 v0 = acc[ai][bj][m][0] * rs, v1 = acc[ai][bj][m][1] * rs;
;                     if (ACT == 1) {
; #pragma unroll
;                         for (int e = 0; e < 4; ++e) { float a = fmaxf(v0[e], 0.f); v0[e] = a * a; float b = fmaxf(v1[e], 0.f); v1[e] = b * b; }
;                     }
;                     u32x4 w; w.x = cvt_pk_bf16(v0[0], v0[1]); w.y = cvt_pk_bf16(v0[2], v0[3]); w.z = cvt_pk_bf16(v1[0], v1[1]); w.w = cvt_pk_bf16(v1[2], v1[3]);
;                     *(u32x4*)(rowp + bj * HALF) = w;
;                 }
; template <class Epi, class Sched, bool ALIGN_EPI = false, bool SP2 = false>
; __device__ __forceinline__ void gemm_phase(PG8_LAS unsigned char* lds, const Gemm g, const Sched& S, const Epi& E) {
;     ...
;         if (!has_next) break;
; #pragma unroll
;         for (int a = 0; a < 2; ++a)
; #pragma unroll
;             for (int b = 0; b < 2; ++b)
; #pragma unroll
;                 for (int m = 0; m < 4; ++m)
; #pragma unroll
;                     for (int n = 0; n < 2; ++n) acc[a][b][m][n] = (f32x4){0.f, 0.f, 0.f, 0.f};
;         cur = nxt; cA = nA; cB = nB; ++ui;
;         if constexpr (ALIGN_EPI) { if (wr == 1) PG8_BAR; }
	v_pk_mul_f32 v[74:75], v[68:69], v[82:83] op_sel_hi:[1,0]
	v_pk_mul_f32 v[68:69], v[66:67], v[82:83] op_sel_hi:[1,0]
	v_cvt_pk_bf16_f32 v66, v70, v71
	v_cvt_pk_bf16_f32 v67, v72, v73
	s_nop 0
	v_cvt_pk_bf16_f32 v68, v68, v69
	v_cvt_pk_bf16_f32 v69, v74, v75
	global_store_dwordx4 v[84:85], v[66:69], off offset:256
	s_nop 1
	v_fmamk_f32 v66, v251, 0x3a000000, v207
	v_rsq_f32_e32 v66, v66
	v_mad_i64_i32 v[68:69], s[4:5], v166, s1, v[152:153]
	v_lshl_add_u64 v[68:69], v[68:69], 0, v[154:155]
	v_pk_mul_f32 v[64:65], v[64:65], v[66:67] op_sel_hi:[1,0]
	v_pk_mul_f32 v[62:63], v[62:63], v[66:67] op_sel_hi:[1,0]
	v_pk_mul_f32 v[70:71], v[60:61], v[66:67] op_sel_hi:[1,0]
	v_pk_mul_f32 v[60:61], v[58:59], v[66:67] op_sel_hi:[1,0]
	v_cvt_pk_bf16_f32 v58, v62, v63
	v_cvt_pk_bf16_f32 v59, v64, v65
	v_pk_mul_f32 v[54:55], v[54:55], v[66:67] op_sel_hi:[1,0]
	v_cvt_pk_bf16_f32 v60, v60, v61
	v_cvt_pk_bf16_f32 v61, v70, v71
	global_store_dwordx4 v[68:69], v[58:61], off
	v_pk_mul_f32 v[56:57], v[56:57], v[66:67] op_sel_hi:[1,0]
	s_nop 0
	v_pk_mul_f32 v[58:59], v[48:49], v[66:67] op_sel_hi:[1,0]
	v_pk_mul_f32 v[48:49], v[46:47], v[66:67] op_sel_hi:[1,0]
	v_cvt_pk_bf16_f32 v46, v54, v55
	v_cvt_pk_bf16_f32 v47, v56, v57
	s_nop 0
	v_cvt_pk_bf16_f32 v48, v48, v49
	v_cvt_pk_bf16_f32 v49, v58, v59
	global_store_dwordx4 v[68:69], v[46:49], off offset:256
	s_nop 1
	v_fmamk_f32 v46, v252, 0x3a000000, v207
	v_rsq_f32_e32 v46, v46
	v_mad_i64_i32 v[48:49], s[4:5], v164, s1, v[152:153]
	v_lshl_add_u64 v[48:49], v[48:49], 0, v[154:155]
	v_pk_mul_f32 v[52:53], v[52:53], v[46:47] op_sel_hi:[1,0]
	v_pk_mul_f32 v[50:51], v[50:51], v[46:47] op_sel_hi:[1,0]
	v_pk_mul_f32 v[54:55], v[44:45], v[46:47] op_sel_hi:[1,0]
	v_pk_mul_f32 v[44:45], v[42:43], v[46:47] op_sel_hi:[1,0]
	v_cvt_pk_bf16_f32 v42, v50, v51
	v_cvt_pk_bf16_f32 v43, v52, v53
	v_pk_mul_f32 v[38:39], v[38:39], v[46:47] op_sel_hi:[1,0]
	v_cvt_pk_bf16_f32 v44, v44, v45
	v_cvt_pk_bf16_f32 v45, v54, v55
	global_store_dwordx4 v[48:49], v[42:45], off
	v_pk_mul_f32 v[40:41], v[40:41], v[46:47] op_sel_hi:[1,0]
	s_nop 0
	v_pk_mul_f32 v[42:43], v[32:33], v[46:47] op_sel_hi:[1,0]
	v_pk_mul_f32 v[32:33], v[30:31], v[46:47] op_sel_hi:[1,0]
	v_cvt_pk_bf16_f32 v30, v38, v39
	v_cvt_pk_bf16_f32 v31, v40, v41
	s_nop 0
	v_cvt_pk_bf16_f32 v32, v32, v33
	v_cvt_pk_bf16_f32 v33, v42, v43
	global_store_dwordx4 v[48:49], v[30:33], off offset:256
	s_nop 1
	v_fmamk_f32 v30, v253, 0x3a000000, v207
	v_rsq_f32_e32 v30, v30
	v_mad_i64_i32 v[32:33], s[4:5], v162, s1, v[152:153]
	v_lshl_add_u64 v[32:33], v[32:33], 0, v[154:155]
	v_pk_mul_f32 v[36:37], v[36:37], v[30:31] op_sel_hi:[1,0]
	v_pk_mul_f32 v[34:35], v[34:35], v[30:31] op_sel_hi:[1,0]
	v_pk_mul_f32 v[38:39], v[28:29], v[30:31] op_sel_hi:[1,0]
	v_pk_mul_f32 v[28:29], v[26:27], v[30:31] op_sel_hi:[1,0]
	v_cvt_pk_bf16_f32 v26, v34, v35
	v_cvt_pk_bf16_f32 v27, v36, v37
	v_pk_mul_f32 v[22:23], v[22:23], v[30:31] op_sel_hi:[1,0]
	v_cvt_pk_bf16_f32 v28, v28, v29
	v_cvt_pk_bf16_f32 v29, v38, v39
	global_store_dwordx4 v[32:33], v[26:29], off
	v_pk_mul_f32 v[24:25], v[24:25], v[30:31] op_sel_hi:[1,0]
	s_nop 0
	v_pk_mul_f32 v[26:27], v[16:17], v[30:31] op_sel_hi:[1,0]
	v_pk_mul_f32 v[16:17], v[14:15], v[30:31] op_sel_hi:[1,0]
	v_cvt_pk_bf16_f32 v14, v22, v23
	v_cvt_pk_bf16_f32 v15, v24, v25
	s_nop 0
	v_cvt_pk_bf16_f32 v16, v16, v17
	v_cvt_pk_bf16_f32 v17, v26, v27
	global_store_dwordx4 v[32:33], v[14:17], off offset:256
	s_nop 1
	v_fmamk_f32 v14, v254, 0x3a000000, v207
	v_rsq_f32_e32 v14, v14
	v_mad_i64_i32 v[16:17], s[4:5], v160, s1, v[152:153]
	v_lshl_add_u64 v[16:17], v[16:17], 0, v[154:155]
	v_pk_mul_f32 v[20:21], v[20:21], v[14:15] op_sel_hi:[1,0]
	v_pk_mul_f32 v[18:19], v[18:19], v[14:15] op_sel_hi:[1,0]
	v_pk_mul_f32 v[22:23], v[12:13], v[14:15] op_sel_hi:[1,0]
	v_pk_mul_f32 v[12:13], v[10:11], v[14:15] op_sel_hi:[1,0]
	v_cvt_pk_bf16_f32 v10, v18, v19
	v_cvt_pk_bf16_f32 v11, v20, v21
	v_pk_mul_f32 v[8:9], v[8:9], v[14:15] op_sel_hi:[1,0]
	v_cvt_pk_bf16_f32 v12, v12, v13
	v_cvt_pk_bf16_f32 v13, v22, v23
	global_store_dwordx4 v[16:17], v[10:13], off
	v_pk_mul_f32 v[6:7], v[6:7], v[14:15] op_sel_hi:[1,0]
	s_nop 0
	v_pk_mul_f32 v[10:11], v[4:5], v[14:15] op_sel_hi:[1,0]
	v_pk_mul_f32 v[4:5], v[2:3], v[14:15] op_sel_hi:[1,0]
	v_cvt_pk_bf16_f32 v2, v6, v7
	v_cvt_pk_bf16_f32 v3, v8, v9
	s_nop 0
	v_cvt_pk_bf16_f32 v4, v4, v5
	v_cvt_pk_bf16_f32 v5, v10, v11
	global_store_dwordx4 v[16:17], v[2:5], off offset:256
	s_cbranch_vccnz .LBB0_261
	s_andn2_b64 vcc, exec, s[42:43]
	s_cbranch_vccnz .LBB0_260
	s_barrier
	s_branch .LBB0_260

; #define PG8_STAGE(bufoff, gbase, voff) do { _Pragma("unroll") for (int _i = 0; _i < 2; ++_i) \
;         __builtin_amdgcn_global_load_lds((const unsigned*)((const char*)(gbase) + (voff)[_i]), (PG8_LAS unsigned*)(lds + (bufoff) + ldsw + _i * 8192), 16, 0, 0); } while (0)
; #define PG8_WAIT_V(n) asm volatile("s_waitcnt vmcnt(" #n ")" ::: "memory")
; template <class Epi, class Sched, bool ALIGN_EPI = false, bool SP2 = false>
; __device__ __forceinline__ void gemm_phase(PG8_LAS unsigned char* lds, const Gemm g, const Sched& S, const Epi& E) {
;     int tid_ = threadIdx.x; asm volatile("" : "+v"(tid_));
;     const int tid = tid_, wid = __builtin_amdgcn_readfirstlane(tid >> 6), lane = tid & 63, wr = wid >> 2, wc = wid & 3, fr = lane & 15, fq = lane >> 4;
;     const int K = g.K, nt = K / BK;
;     unsigned voffA[2], voffB[2];
; #pragma unroll
;     for (int i = 0; i < 2; ++i) { int R, C; stage_rc(tid * 16 + i * 8192, R, C); const int Rb = Epi::PERM ? ((R & ~31) + perm32(R & 31)) : R;
;         voffA[i] = (unsigned)(R * K + C) * 2u; voffB[i] = (unsigned)(Rb * K + C) * 2u; }
;     const size_t kstep = (size_t)(BK * 2);
;     const size_t hstep = (size_t)HALF * K * 2;
;     const size_t tstep = 2 * hstep;
;     const unsigned ldsw = (unsigned)wid * 1024u;
;     const int aoff = lds_byte(wr * 64 + fr, fq * 8), boff = lds_byte(wc * 32 + fr, fq * 8);
;     ...
;     Unit cur, nxt; int ui = 0;
;     if (!S.next(0, cur)) return;
;     f32x4 acc[2][2][4][2];
; #pragma unroll
;     for (int a = 0; a < 2; ++a)
; #pragma unroll
;         for (int b = 0; b < 2; ++b)
; #pragma unroll
;             for (int m = 0; m < 4; ++m)
; #pragma unroll
;                 for (int n = 0; n < 2; ++n) acc[a][b][m][n] = (f32x4){0.f, 0.f, 0.f, 0.f};
;     bf16x8 At[4][2], B0[2][2], B1[2][2];
;     const char* cA = (const char*)g.A + (size_t)cur.pm * tstep; const char* cB = (const char*)g.Bt + (size_t)cur.pn * tstep;
;     S.a_ready(cur);
;     if constexpr (SP2) {
;         PG8_STAGE(PG8_SB(0, 0), cB, voffB); PG8_STAGE(PG8_SB(0, 1), cB + hstep, voffB); PG8_STAGE(PG8_SA(0, 0), cA, voffA); PG8_STAGE(PG8_SA(0, 1), cA + hstep, voffA);
;         if (wr == 1) PG8_BAR;
;         PG8_WAIT_V(2); PG8_BAR;
;         PG8_STAGE(PG8_SB(1, 0), cB + kstep, voffB); PG8_STAGE(PG8_SA(1, 0), cA + kstep, voffA); PG8_STAGE(PG8_SB(1, 1), cB + hstep + kstep, voffB);
;         PG8_WAIT_V(6); PG8_BAR;
.LBB0_673:
	s_or_b64 exec, exec, s[16:17]
	v_readlane_b32 s4, v245, 38
	s_mov_b64 s[16:17], s[72:73]
	v_mov_b32_e32 v16, v202
	v_readlane_b32 s5, v245, 39
	s_waitcnt lgkmcnt(0)
	s_barrier
	s_andn2_b64 vcc, exec, s[4:5]
	v_readfirstlane_b32 s2, v16
	s_cbranch_vccnz .LBB0_693
	v_lshlrev_b32_e32 v0, 4, v16
	v_add_u32_e32 v2, 0x2000, v0
	v_ashrrev_i32_e32 v3, 31, v2
	v_lshrrev_b32_e32 v3, 22, v3
	v_add_u32_e32 v3, v2, v3
	v_ashrrev_i32_e32 v10, 10, v3
	v_mul_i32_i24_e32 v3, 0x400, v10
	v_sub_u32_e32 v2, v2, v3
	v_lshrrev_b32_e32 v3, 4, v2
	v_bitop3_b32 v2, v3, v2, 32 bitop3:0x6c
	v_ashrrev_i32_e32 v3, 31, v2
	v_lshrrev_b32_e32 v3, 26, v3
	v_add_u32_e32 v3, v2, v3
	v_lshlrev_b32_e32 v4, 3, v10
	v_ashrrev_i32_e32 v11, 6, v3
	v_and_b32_e32 v4, -16, v4
	v_add_u32_e32 v4, v11, v4
	v_and_b32_e32 v5, 3, v11
	s_mov_b32 s7, 0xfffe0
	v_lshrrev_b32_e32 v6, 2, v4
	v_lshlrev_b32_e32 v7, 1, v4
	v_and_b32_e32 v3, 0xc0, v3
	v_and_or_b32 v5, v4, s7, v5
	v_and_b32_e32 v6, 4, v6
	v_and_b32_e32 v7, 24, v7
	v_sub_u32_e32 v2, v2, v3
	v_or3_b32 v5, v5, v6, v7
	v_lshlrev_b32_e32 v6, 5, v10
	v_ashrrev_i16_sdwa v2, v206, sext(v2) dst_sel:DWORD dst_unused:UNUSED_PAD src0_sel:DWORD src1_sel:BYTE_0
	v_and_b32_e32 v6, 32, v6
	v_bfe_i32 v12, v2, 0, 16
	v_add_lshl_u32 v2, v6, v12, 1
	v_lshl_add_u32 v142, v5, 12, v2
	v_lshl_add_u32 v144, v4, 12, v2
	v_bfe_i32 v2, v16, 27, 1
	v_lshrrev_b32_e32 v2, 22, v2
	v_add_u32_e32 v2, v0, v2
	v_and_b32_e32 v2, 0xfffffc00, v2
	v_sub_u32_e32 v0, v0, v2
	s_load_dwordx2 s[24:25], s[16:17], 0x80
	v_lshrrev_b32_e32 v2, 4, v0
	v_ashrrev_i32_e32 v3, 31, v16
	v_bitop3_b32 v0, v2, v0, 32 bitop3:0x6c
	v_lshrrev_b32_e32 v3, 26, v3
	v_ashrrev_i32_e32 v2, 31, v0
	v_add_u32_e32 v3, v16, v3
	v_lshrrev_b32_e32 v2, 26, v2
	v_ashrrev_i32_e32 v14, 6, v3
	v_add_u32_e32 v2, v0, v2
	v_lshlrev_b32_e32 v3, 3, v14
	s_waitcnt lgkmcnt(0)
	s_add_u32 s26, s24, 0x6400000
	v_ashrrev_i32_e32 v13, 6, v2
	v_and_b32_e32 v3, -16, v3
	s_addc_u32 s27, s25, 0
	v_add_u32_e32 v3, v13, v3
	s_add_u32 s28, s24, 0x2400000
	v_and_b32_e32 v4, 3, v13
	v_lshrrev_b32_e32 v5, 2, v3
	v_lshlrev_b32_e32 v6, 1, v3
	v_and_b32_e32 v2, 0xc0, v2
	s_addc_u32 s29, s25, 0
	s_ashr_i32 s4, s2, 6
	v_and_or_b32 v4, v3, s7, v4
	v_and_b32_e32 v5, 4, v5
	v_and_b32_e32 v6, 24, v6
	v_sub_u32_e32 v0, v0, v2
	s_ashr_i32 s5, s2, 8
	s_lshl_b32 s58, s4, 10
	v_or3_b32 v4, v4, v5, v6
	v_lshlrev_b32_e32 v5, 5, v14
	v_ashrrev_i16_sdwa v0, v206, sext(v0) dst_sel:DWORD dst_unused:UNUSED_PAD src0_sel:DWORD src1_sel:BYTE_0
	v_readlane_b32 s8, v245, 57
	v_and_b32_e32 v5, 32, v5
	v_bfe_i32 v15, v0, 0, 16
	v_readlane_b32 s9, v245, 58
	s_add_u32 s18, s28, s8
	v_add_lshl_u32 v2, v5, v15, 1
	s_addc_u32 s19, s29, s9
	s_add_i32 s59, s58, 0
	v_lshl_add_u32 v0, v4, 12, v2
	s_add_i32 m0, s59, 0x10000
	v_lshl_add_u32 v146, v3, 12, v2
	global_load_lds_dwordx4 v0, s[18:19]
	s_add_i32 m0, s59, 0x12000
	s_add_u32 s8, s18, 0x80000
	global_load_lds_dwordx4 v142, s[18:19]
	s_addc_u32 s9, s19, 0
	s_add_i32 m0, s59, 0x14000
	v_mov_b32_e32 v143, v1
	global_load_lds_dwordx4 v0, s[8:9]
	s_add_i32 m0, s59, 0x16000
	v_mov_b32_e32 v147, v1
	global_load_lds_dwordx4 v142, s[8:9]
	v_readlane_b32 s8, v244, 2
	v_readlane_b32 s9, v244, 3
	s_add_u32 s16, s26, s8
	s_addc_u32 s17, s27, s9
	s_add_i32 s60, s59, 0x2000
	s_mov_b32 m0, s59
	s_add_u32 s8, s16, 0x80000
	global_load_lds_dwordx4 v146, s[16:17]
	s_mov_b32 m0, s60
	s_addc_u32 s9, s17, 0
	s_add_i32 s61, s59, 0x4000
	global_load_lds_dwordx4 v144, s[16:17]
	s_mov_b32 m0, s61
	s_add_i32 s62, s59, 0x6000
	global_load_lds_dwordx4 v146, s[8:9]
	s_mov_b32 m0, s62
	v_mov_b32_e32 v145, v1
	global_load_lds_dwordx4 v144, s[8:9]
	s_cmp_eq_u32 s5, 1
	v_lshl_add_u64 v[8:9], s[18:19], 0, v[0:1]
	v_lshl_add_u64 v[6:7], s[18:19], 0, v[142:143]
	v_lshl_add_u64 v[2:3], s[16:17], 0, v[146:147]
	s_cselect_b64 s[44:45], -1, 0
	s_cmp_lg_u32 s5, 1
	v_lshl_add_u64 v[4:5], s[16:17], 0, v[144:145]
	s_cbranch_scc1 .LBB0_676
	s_barrier

;     __host__ __device__ bool next(int i, Unit& u) const {
;         const long L = (long)i * G + c; if (L >= nwg) return false;
;         int wgid = (int)L; { const int q = nwg / NXCD, r = nwg % NXCD, xcd = wgid % NXCD, off = wgid / NXCD; wgid = (xcd < r ? xcd * (q + 1) : r * (q + 1) + (xcd - r) * q) + off; }
;         const int nig = wgm * nN, gid = wgid / nig, fm = gid * wgm, gsz = (nM - fm) < wgm ? (nM - fm) : wgm;
;         u.pm = fm + ((wgid % nig) % gsz); u.pn = (wgid % nig) / gsz; return true;
; template <class Epi, class Sched, bool ALIGN_EPI = false, bool SP2 = false>
; __device__ __forceinline__ void gemm_phase(PG8_LAS unsigned char* lds, const Gemm g, const Sched& S, const Epi& E) {
;     ...
;         const bool has_next = S.next(ui + 1, nxt);
.LBB0_679:
	v_lshl_add_u32 v200, s4, 8, v162
	v_ashrrev_i32_e32 v201, 31, v200
	v_lshl_add_u64 v[200:201], v[200:201], 2, s[46:47]
	global_load_dword v247, v[200:201], off
	global_load_dword v248, v[200:201], off offset:64
	global_load_dword v249, v[200:201], off offset:128
	global_load_dword v250, v[200:201], off offset:192
	global_load_dword v251, v[200:201], off offset:512
	global_load_dword v252, v[200:201], off offset:576
	global_load_dword v253, v[200:201], off offset:640
	global_load_dword v254, v[200:201], off offset:704
	s_add_i32 s65, s65, 1
	s_mul_i32 s5, s65, s33
	s_mul_hi_u32 s7, s65, s70
	s_add_i32 s7, s7, s5
	s_mul_i32 s5, s65, s70
	s_add_u32 s24, s5, s6
	s_addc_u32 s25, s7, s97
	v_cmp_gt_i64_e32 vcc, s[24:25], v[140:141]
	v_cmp_lt_i64_e64 s[42:43], s[24:25], v[138:139]
	s_cbranch_vccnz .LBB0_685
	s_ashr_i32 s5, s24, 31
	s_lshr_b32 s5, s5, 29
	s_add_i32 s5, s24, s5
	s_and_b32 s7, s5, -8
	s_sub_i32 s7, s24, s7
	s_cmp_gt_i32 s7, -1
	s_mov_b64 s[24:25], -1
	s_cbranch_scc0 .LBB0_682
	s_lshl_b32 s8, s7, 8
	s_mov_b64 s[24:25], 0

; __device__ __forceinline__ unsigned cvt_pk_bf16(float lo, float hi) { unsigned r; asm volatile("v_cvt_pk_bf16_f32 %0, %1, %2" : "=v"(r) : "v"(lo), "v"(hi)); return r; }
;     __device__ __forceinline__ void operator()(const f32x4 (&acc)[2][2][4][2], const Unit& u, int wr, int wc, int fr, int fq) const {
;     ...
;         for (int ai = 0; ai < 2; ++ai)
; #pragma unroll
;             for (int m = 0; m < 4; ++m) {
;                 const int row = row0 + ai * HALF + m * 16;
;                 const float rs = __builtin_amdgcn_rsqf(sv[ai][m] * (1.0f / 2048.0f) + 1e-6f);
;                 bf16_t* rowp = O + (size_t)row * ldc + col0;
; #pragma unroll
;                 for (int bj = 0; bj < 2; ++bj) {
;                     f32x4 v0 = acc[ai][bj][m][0] * rs, v1 = acc[ai][bj][m][1] * rs;
;                     if (ACT == 1) {
; #pragma unroll
;                         for (int e = 0; e < 4; ++e) { float a = fmaxf(v0[e], 0.f); v0[e] = a * a; float b = fmaxf(v1[e], 0.f); v1[e] = b * b; }
;                     }
;                     u32x4 w; w.x = cvt_pk_bf16(v0[0], v0[1]); w.y = cvt_pk_bf16(v0[2], v0[3]); w.z = cvt_pk_bf16(v1[0], v1[1]); w.w = cvt_pk_bf16(v1[2], v1[3]);
;                     *(u32x4*)(rowp + bj * HALF) = w;
;                 }
.LBB0_689:
	v_lshl_add_u32 v152, s4, 8, v162
	v_ashrrev_i32_e32 v153, 31, v152
	v_lshl_add_u64 v[158:159], v[152:153], 2, s[46:47]
	v_lshl_or_b32 v158, s2, 8, v164
	v_or_b32_e32 v160, 16, v152
	v_or_b32_e32 v156, 32, v152
	v_or_b32_e32 v154, 48, v152
	v_ashrrev_i32_e32 v159, 31, v158
	v_lshlrev_b64 v[152:153], 14, v[152:153]
	v_lshl_add_u64 v[152:153], s[48:49], 0, v[152:153]
	v_lshlrev_b64 v[158:159], 1, v[158:159]
	v_lshl_add_u64 v[152:153], v[152:153], 0, v[158:159]
	v_ashrrev_i32_e32 v161, 31, v160
	v_ashrrev_i32_e32 v157, 31, v156
	v_ashrrev_i32_e32 v155, 31, v154
	s_mov_b32 s2, 0x200000
	s_mov_b64 s[4:5], 0x200000
	s_mov_b64 s[16:17], -1
	v_fmamk_f32 v172, v247, 0x3a000000, v207
	v_rsq_f32_e32 v172, v172
	s_nop 0
	v_pk_mul_f32 v[122:123], v[122:123], v[172:173] op_sel_hi:[1,0]
	v_pk_mul_f32 v[126:127], v[126:127], v[172:173] op_sel_hi:[1,0]
	v_pk_mul_f32 v[124:125], v[124:125], v[172:173] op_sel_hi:[1,0]
	v_max_f32_e32 v122, 0, v122
	v_pk_mul_f32 v[128:129], v[128:129], v[172:173] op_sel_hi:[1,0]
	v_mul_f32_e32 v174, v122, v122
	v_max_f32_e32 v122, 0, v127
	v_max_f32_e32 v123, 0, v123
	v_max_f32_e32 v124, 0, v124
	v_max_f32_e32 v126, 0, v126
	v_mul_f32_e32 v122, v122, v122
	v_mul_f32_e32 v127, v123, v123
	v_max_f32_e32 v123, 0, v128
	v_mul_f32_e32 v128, v124, v124
	v_max_f32_e32 v124, 0, v129
	v_max_f32_e32 v125, 0, v125
	v_pk_mul_f32 v[114:115], v[114:115], v[172:173] op_sel_hi:[1,0]
	v_mul_f32_e32 v126, v126, v126
	v_mul_f32_e32 v123, v123, v123
	v_mul_f32_e32 v124, v124, v124
	v_mul_f32_e32 v125, v125, v125
	v_cvt_pk_bf16_f32 v122, v126, v122
	v_pk_mul_f32 v[118:119], v[118:119], v[172:173] op_sel_hi:[1,0]
	v_pk_mul_f32 v[116:117], v[116:117], v[172:173] op_sel_hi:[1,0]
	v_max_f32_e32 v114, 0, v114
	v_cvt_pk_bf16_f32 v123, v123, v124
	v_cvt_pk_bf16_f32 v124, v174, v127
	v_cvt_pk_bf16_f32 v125, v128, v125
	global_store_dwordx4 v[152:153], v[122:125], off
	v_pk_mul_f32 v[120:121], v[120:121], v[172:173] op_sel_hi:[1,0]
	v_max_f32_e32 v115, 0, v115
	v_mul_f32_e32 v122, v114, v114
	v_max_f32_e32 v114, 0, v119
	v_max_f32_e32 v116, 0, v116
	v_max_f32_e32 v118, 0, v118
	v_mul_f32_e32 v114, v114, v114
	v_mul_f32_e32 v119, v115, v115
	v_max_f32_e32 v115, 0, v120
	v_mul_f32_e32 v120, v116, v116
	v_max_f32_e32 v116, 0, v121
	v_max_f32_e32 v117, 0, v117
	v_mul_f32_e32 v118, v118, v118
	v_mul_f32_e32 v115, v115, v115
	v_mul_f32_e32 v116, v116, v116
	v_mul_f32_e32 v117, v117, v117
	v_cvt_pk_bf16_f32 v114, v118, v114
	v_cvt_pk_bf16_f32 v115, v115, v116
	v_cvt_pk_bf16_f32 v116, v122, v119
	v_cvt_pk_bf16_f32 v117, v120, v117
	global_store_dwordx4 v[152:153], v[114:117], off offset:256
	s_nop 1
	v_fmamk_f32 v114, v248, 0x3a000000, v207
	v_rsq_f32_e32 v114, v114
	v_lshlrev_b64 v[116:117], 14, v[160:161]
	v_lshl_add_u64 v[116:117], s[48:49], 0, v[116:117]
	v_lshl_add_u64 v[116:117], v[116:117], 0, v[158:159]
	v_pk_mul_f32 v[106:107], v[106:107], v[114:115] op_sel_hi:[1,0]
	v_pk_mul_f32 v[110:111], v[110:111], v[114:115] op_sel_hi:[1,0]
	v_pk_mul_f32 v[108:109], v[108:109], v[114:115] op_sel_hi:[1,0]
	v_max_f32_e32 v106, 0, v106
	v_pk_mul_f32 v[112:113], v[112:113], v[114:115] op_sel_hi:[1,0]
	v_mul_f32_e32 v115, v106, v106
	v_max_f32_e32 v106, 0, v111
	v_max_f32_e32 v107, 0, v107
	v_max_f32_e32 v108, 0, v108
	v_max_f32_e32 v110, 0, v110
	v_mul_f32_e32 v106, v106, v106
	v_mul_f32_e32 v111, v107, v107
	v_max_f32_e32 v107, 0, v112
	v_mul_f32_e32 v112, v108, v108
	v_max_f32_e32 v108, 0, v113
	v_max_f32_e32 v109, 0, v109
	v_pk_mul_f32 v[98:99], v[98:99], v[114:115] op_sel_hi:[1,0]
	v_mul_f32_e32 v110, v110, v110
	v_mul_f32_e32 v107, v107, v107
	v_mul_f32_e32 v108, v108, v108
	v_mul_f32_e32 v109, v109, v109
	v_cvt_pk_bf16_f32 v106, v110, v106
	v_pk_mul_f32 v[102:103], v[102:103], v[114:115] op_sel_hi:[1,0]
	v_pk_mul_f32 v[100:101], v[100:101], v[114:115] op_sel_hi:[1,0]
	v_max_f32_e32 v98, 0, v98
	v_cvt_pk_bf16_f32 v107, v107, v108
	v_cvt_pk_bf16_f32 v108, v115, v111
	v_cvt_pk_bf16_f32 v109, v112, v109
	global_store_dwordx4 v[116:117], v[106:109], off
	v_pk_mul_f32 v[104:105], v[104:105], v[114:115] op_sel_hi:[1,0]
	v_max_f32_e32 v99, 0, v99
	v_mul_f32_e32 v106, v98, v98
	v_max_f32_e32 v98, 0, v103
	v_max_f32_e32 v100, 0, v100
	v_max_f32_e32 v102, 0, v102
	v_mul_f32_e32 v98, v98, v98
	v_mul_f32_e32 v103, v99, v99
	v_max_f32_e32 v99, 0, v104
	v_mul_f32_e32 v104, v100, v100
	v_max_f32_e32 v100, 0, v105
	v_max_f32_e32 v101, 0, v101
	v_mul_f32_e32 v102, v102, v102
	v_mul_f32_e32 v99, v99, v99
	v_mul_f32_e32 v100, v100, v100
	v_mul_f32_e32 v101, v101, v101
	v_cvt_pk_bf16_f32 v98, v102, v98
	v_cvt_pk_bf16_f32 v99, v99, v100
	v_cvt_pk_bf16_f32 v100, v106, v103
	v_cvt_pk_bf16_f32 v101, v104, v101
	global_store_dwordx4 v[116:117], v[98:101], off offset:256
	s_nop 1
	v_fmamk_f32 v98, v249, 0x3a000000, v207
	v_rsq_f32_e32 v98, v98
	v_lshlrev_b64 v[100:101], 14, v[156:157]
	v_lshl_add_u64 v[100:101], s[48:49], 0, v[100:101]
	v_lshl_add_u64 v[100:101], v[100:101], 0, v[158:159]
	v_pk_mul_f32 v[90:91], v[90:91], v[98:99] op_sel_hi:[1,0]
	v_pk_mul_f32 v[94:95], v[94:95], v[98:99] op_sel_hi:[1,0]
	v_pk_mul_f32 v[92:93], v[92:93], v[98:99] op_sel_hi:[1,0]
	v_max_f32_e32 v90, 0, v90
	v_pk_mul_f32 v[96:97], v[96:97], v[98:99] op_sel_hi:[1,0]
	v_mul_f32_e32 v99, v90, v90
	v_max_f32_e32 v90, 0, v95
	v_max_f32_e32 v91, 0, v91
	v_max_f32_e32 v92, 0, v92
	v_max_f32_e32 v94, 0, v94
	v_mul_f32_e32 v90, v90, v90
	v_mul_f32_e32 v95, v91, v91
	v_max_f32_e32 v91, 0, v96
	v_mul_f32_e32 v96, v92, v92
	v_max_f32_e32 v92, 0, v97
	v_max_f32_e32 v93, 0, v93
	v_pk_mul_f32 v[82:83], v[82:83], v[98:99] op_sel_hi:[1,0]
	v_mul_f32_e32 v94, v94, v94
	v_mul_f32_e32 v91, v91, v91
; __device__ __forceinline__ unsigned cvt_pk_bf16(float lo, float hi) { unsigned r; asm volatile("v_cvt_pk_bf16_f32 %0, %1, %2" : "=v"(r) : "v"(lo), "v"(hi)); return r; }
;     __device__ __forceinline__ void operator()(const f32x4 (&acc)[2][2][4][2], const Unit& u, int wr, int wc, int fr, int fq) const {
;     ...
;         for (int ai = 0; ai < 2; ++ai)
; #pragma unroll
;             for (int m = 0; m < 4; ++m) {
;                 const int row = row0 + ai * HALF + m * 16;
;                 const float rs = __builtin_amdgcn_rsqf(sv[ai][m] * (1.0f / 2048.0f) + 1e-6f);
;                 bf16_t* rowp = O + (size_t)row * ldc + col0;
; #pragma unroll
;                 for (int bj = 0; bj < 2; ++bj) {
;                     f32x4 v0 = acc[ai][bj][m][0] * rs, v1 = acc[ai][bj][m][1] * rs;
;                     if (ACT == 1) {
; #pragma unroll
;                         for (int e = 0; e < 4; ++e) { float a = fmaxf(v0[e], 0.f); v0[e] = a * a; float b = fmaxf(v1[e], 0.f); v1[e] = b * b; }
;                     }
;                     u32x4 w; w.x = cvt_pk_bf16(v0[0], v0[1]); w.y = cvt_pk_bf16(v0[2], v0[3]); w.z = cvt_pk_bf16(v1[0], v1[1]); w.w = cvt_pk_bf16(v1[2], v1[3]);
;                     *(u32x4*)(rowp + bj * HALF) = w;
;                 }
	v_mul_f32_e32 v92, v92, v92
	v_mul_f32_e32 v93, v93, v93
	v_cvt_pk_bf16_f32 v90, v94, v90
	v_pk_mul_f32 v[86:87], v[86:87], v[98:99] op_sel_hi:[1,0]
	v_pk_mul_f32 v[84:85], v[84:85], v[98:99] op_sel_hi:[1,0]
	v_max_f32_e32 v82, 0, v82
	v_cvt_pk_bf16_f32 v91, v91, v92
	v_cvt_pk_bf16_f32 v92, v99, v95
	v_cvt_pk_bf16_f32 v93, v96, v93
	global_store_dwordx4 v[100:101], v[90:93], off
	v_pk_mul_f32 v[88:89], v[88:89], v[98:99] op_sel_hi:[1,0]
	v_max_f32_e32 v83, 0, v83
	v_mul_f32_e32 v90, v82, v82
	v_max_f32_e32 v82, 0, v87
	v_max_f32_e32 v84, 0, v84
	v_max_f32_e32 v86, 0, v86
	v_mul_f32_e32 v82, v82, v82
	v_mul_f32_e32 v87, v83, v83
	v_max_f32_e32 v83, 0, v88
	v_mul_f32_e32 v88, v84, v84
	v_max_f32_e32 v84, 0, v89
	v_max_f32_e32 v85, 0, v85
	v_mul_f32_e32 v86, v86, v86
	v_mul_f32_e32 v83, v83, v83
	v_mul_f32_e32 v84, v84, v84
	v_mul_f32_e32 v85, v85, v85
	v_cvt_pk_bf16_f32 v82, v86, v82
	v_cvt_pk_bf16_f32 v83, v83, v84
	v_cvt_pk_bf16_f32 v84, v90, v87
	v_cvt_pk_bf16_f32 v85, v88, v85
	global_store_dwordx4 v[100:101], v[82:85], off offset:256
	s_nop 1
	v_fmamk_f32 v82, v250, 0x3a000000, v207
	v_rsq_f32_e32 v82, v82
	v_lshlrev_b64 v[84:85], 14, v[154:155]
	v_lshl_add_u64 v[84:85], s[48:49], 0, v[84:85]
	v_lshl_add_u64 v[84:85], v[84:85], 0, v[158:159]
	v_pk_mul_f32 v[74:75], v[74:75], v[82:83] op_sel_hi:[1,0]
	v_pk_mul_f32 v[78:79], v[78:79], v[82:83] op_sel_hi:[1,0]
	v_pk_mul_f32 v[76:77], v[76:77], v[82:83] op_sel_hi:[1,0]
	v_max_f32_e32 v74, 0, v74
	v_pk_mul_f32 v[80:81], v[80:81], v[82:83] op_sel_hi:[1,0]
	v_mul_f32_e32 v83, v74, v74
	v_max_f32_e32 v74, 0, v79
	v_max_f32_e32 v75, 0, v75
	v_max_f32_e32 v76, 0, v76
	v_max_f32_e32 v78, 0, v78
	v_mul_f32_e32 v74, v74, v74
	v_mul_f32_e32 v79, v75, v75
	v_max_f32_e32 v75, 0, v80
	v_mul_f32_e32 v80, v76, v76
	v_max_f32_e32 v76, 0, v81
	v_max_f32_e32 v77, 0, v77
	v_pk_mul_f32 v[66:67], v[66:67], v[82:83] op_sel_hi:[1,0]
	v_mul_f32_e32 v78, v78, v78
	v_mul_f32_e32 v75, v75, v75
	v_mul_f32_e32 v76, v76, v76
	v_mul_f32_e32 v77, v77, v77
	v_cvt_pk_bf16_f32 v74, v78, v74
	v_pk_mul_f32 v[70:71], v[70:71], v[82:83] op_sel_hi:[1,0]
	v_pk_mul_f32 v[68:69], v[68:69], v[82:83] op_sel_hi:[1,0]
	v_max_f32_e32 v66, 0, v66
	v_cvt_pk_bf16_f32 v75, v75, v76
	v_cvt_pk_bf16_f32 v76, v83, v79
	v_cvt_pk_bf16_f32 v77, v80, v77
	global_store_dwordx4 v[84:85], v[74:77], off
	v_pk_mul_f32 v[72:73], v[72:73], v[82:83] op_sel_hi:[1,0]
	v_max_f32_e32 v67, 0, v67
	v_mul_f32_e32 v74, v66, v66
	v_max_f32_e32 v66, 0, v71
	v_max_f32_e32 v68, 0, v68
	v_max_f32_e32 v70, 0, v70
	v_mul_f32_e32 v66, v66, v66
	v_mul_f32_e32 v71, v67, v67
	v_max_f32_e32 v67, 0, v72
	v_mul_f32_e32 v72, v68, v68
	v_max_f32_e32 v68, 0, v73
	v_max_f32_e32 v69, 0, v69
	v_mul_f32_e32 v70, v70, v70
	v_mul_f32_e32 v67, v67, v67
	v_mul_f32_e32 v68, v68, v68
	v_mul_f32_e32 v69, v69, v69
	v_cvt_pk_bf16_f32 v66, v70, v66
	v_cvt_pk_bf16_f32 v67, v67, v68
	v_cvt_pk_bf16_f32 v68, v74, v71
	v_cvt_pk_bf16_f32 v69, v72, v69
	global_store_dwordx4 v[84:85], v[66:69], off offset:256
	s_nop 1
	v_fmamk_f32 v66, v251, 0x3a000000, v207
	v_rsq_f32_e32 v66, v66
	v_lshl_add_u64 v[68:69], v[152:153], 0, s[4:5]
	s_mov_b64 s[4:5], 0x240000
	v_pk_mul_f32 v[58:59], v[58:59], v[66:67] op_sel_hi:[1,0]
	v_pk_mul_f32 v[62:63], v[62:63], v[66:67] op_sel_hi:[1,0]
	v_pk_mul_f32 v[60:61], v[60:61], v[66:67] op_sel_hi:[1,0]
	v_max_f32_e32 v58, 0, v58
	v_pk_mul_f32 v[64:65], v[64:65], v[66:67] op_sel_hi:[1,0]
	v_max_f32_e32 v62, 0, v62
	v_mul_f32_e32 v67, v58, v58
	v_max_f32_e32 v58, 0, v63
	v_max_f32_e32 v59, 0, v59
	v_max_f32_e32 v60, 0, v60
	v_mul_f32_e32 v62, v62, v62
	v_mul_f32_e32 v58, v58, v58
	v_mul_f32_e32 v63, v59, v59
	v_max_f32_e32 v59, 0, v64
	v_mul_f32_e32 v64, v60, v60
	v_max_f32_e32 v60, 0, v65
	v_mul_f32_e32 v59, v59, v59
	v_mul_f32_e32 v60, v60, v60
	v_max_f32_e32 v61, 0, v61
	v_cvt_pk_bf16_f32 v58, v62, v58
	v_add_co_u32_e32 v62, vcc, s2, v152
	v_pk_mul_f32 v[50:51], v[50:51], v[66:67] op_sel_hi:[1,0]
	v_mul_f32_e32 v61, v61, v61
	v_cvt_pk_bf16_f32 v59, v59, v60
	v_cvt_pk_bf16_f32 v60, v67, v63
	v_addc_co_u32_e32 v63, vcc, 0, v153, vcc
	v_pk_mul_f32 v[54:55], v[54:55], v[66:67] op_sel_hi:[1,0]
	v_pk_mul_f32 v[52:53], v[52:53], v[66:67] op_sel_hi:[1,0]
	v_max_f32_e32 v50, 0, v50
	v_cvt_pk_bf16_f32 v61, v64, v61
	global_store_dwordx4 v[62:63], v[58:61], off
	v_pk_mul_f32 v[56:57], v[56:57], v[66:67] op_sel_hi:[1,0]
	v_max_f32_e32 v51, 0, v51
	v_mul_f32_e32 v58, v50, v50
	v_max_f32_e32 v50, 0, v55
	v_max_f32_e32 v52, 0, v52
	v_max_f32_e32 v54, 0, v54
	v_mul_f32_e32 v50, v50, v50
	v_mul_f32_e32 v55, v51, v51
	v_max_f32_e32 v51, 0, v56
	v_mul_f32_e32 v56, v52, v52
	v_max_f32_e32 v52, 0, v57
	v_max_f32_e32 v53, 0, v53
	v_mul_f32_e32 v54, v54, v54
	v_mul_f32_e32 v51, v51, v51
	v_mul_f32_e32 v52, v52, v52
	v_mul_f32_e32 v53, v53, v53
	v_cvt_pk_bf16_f32 v50, v54, v50
	v_cvt_pk_bf16_f32 v51, v51, v52
	v_cvt_pk_bf16_f32 v52, v58, v55
	v_cvt_pk_bf16_f32 v53, v56, v53
	global_store_dwordx4 v[68:69], v[50:53], off offset:256
	s_mov_b32 s2, 0x240000
	s_nop 0
	v_fmamk_f32 v50, v252, 0x3a000000, v207
	v_rsq_f32_e32 v50, v50
	v_lshl_add_u64 v[52:53], v[152:153], 0, s[4:5]
	s_mov_b64 s[4:5], 0x280000
	v_pk_mul_f32 v[42:43], v[42:43], v[50:51] op_sel_hi:[1,0]
	v_pk_mul_f32 v[46:47], v[46:47], v[50:51] op_sel_hi:[1,0]
	v_pk_mul_f32 v[44:45], v[44:45], v[50:51] op_sel_hi:[1,0]
	v_max_f32_e32 v42, 0, v42
	v_pk_mul_f32 v[48:49], v[48:49], v[50:51] op_sel_hi:[1,0]
	v_max_f32_e32 v46, 0, v46
	v_mul_f32_e32 v51, v42, v42
	v_max_f32_e32 v42, 0, v47
; __device__ __forceinline__ unsigned cvt_pk_bf16(float lo, float hi) { unsigned r; asm volatile("v_cvt_pk_bf16_f32 %0, %1, %2" : "=v"(r) : "v"(lo), "v"(hi)); return r; }
; #define PG8_BAR __builtin_amdgcn_s_barrier()
;     __device__ __forceinline__ void operator()(const f32x4 (&acc)[2][2][4][2], const Unit& u, int wr, int wc, int fr, int fq) const {
;     ...
;         for (int ai = 0; ai < 2; ++ai)
; #pragma unroll
;             for (int m = 0; m < 4; ++m) {
;                 const int row = row0 + ai * HALF + m * 16;
;                 const float rs = __builtin_amdgcn_rsqf(sv[ai][m] * (1.0f / 2048.0f) + 1e-6f);
;                 bf16_t* rowp = O + (size_t)row * ldc + col0;
; #pragma unroll
;                 for (int bj = 0; bj < 2; ++bj) {
;                     f32x4 v0 = acc[ai][bj][m][0] * rs, v1 = acc[ai][bj][m][1] * rs;
;                     if (ACT == 1) {
; #pragma unroll
;                         for (int e = 0; e < 4; ++e) { float a = fmaxf(v0[e], 0.f); v0[e] = a * a; float b = fmaxf(v1[e], 0.f); v1[e] = b * b; }
;                     }
;                     u32x4 w; w.x = cvt_pk_bf16(v0[0], v0[1]); w.y = cvt_pk_bf16(v0[2], v0[3]); w.z = cvt_pk_bf16(v1[0], v1[1]); w.w = cvt_pk_bf16(v1[2], v1[3]);
;                     *(u32x4*)(rowp + bj * HALF) = w;
;                 }
; template <class Epi, class Sched, bool ALIGN_EPI = false, bool SP2 = false>
; __device__ __forceinline__ void gemm_phase(PG8_LAS unsigned char* lds, const Gemm g, const Sched& S, const Epi& E) {
;     ...
;         if (!has_next) break;
; #pragma unroll
;         for (int a = 0; a < 2; ++a)
; #pragma unroll
;             for (int b = 0; b < 2; ++b)
; #pragma unroll
;                 for (int m = 0; m < 4; ++m)
; #pragma unroll
;                     for (int n = 0; n < 2; ++n) acc[a][b][m][n] = (f32x4){0.f, 0.f, 0.f, 0.f};
;         cur = nxt; cA = nA; cB = nB; ++ui;
;         if constexpr (ALIGN_EPI) { if (wr == 1) PG8_BAR; }
	v_max_f32_e32 v43, 0, v43
	v_max_f32_e32 v44, 0, v44
	v_mul_f32_e32 v46, v46, v46
	v_mul_f32_e32 v42, v42, v42
	v_mul_f32_e32 v47, v43, v43
	v_max_f32_e32 v43, 0, v48
	v_mul_f32_e32 v48, v44, v44
	v_max_f32_e32 v44, 0, v49
	v_mul_f32_e32 v43, v43, v43
	v_mul_f32_e32 v44, v44, v44
	v_max_f32_e32 v45, 0, v45
	v_cvt_pk_bf16_f32 v42, v46, v42
	v_add_co_u32_e32 v46, vcc, s2, v152
	v_pk_mul_f32 v[34:35], v[34:35], v[50:51] op_sel_hi:[1,0]
	v_mul_f32_e32 v45, v45, v45
	v_cvt_pk_bf16_f32 v43, v43, v44
	v_cvt_pk_bf16_f32 v44, v51, v47
	v_addc_co_u32_e32 v47, vcc, 0, v153, vcc
	v_pk_mul_f32 v[38:39], v[38:39], v[50:51] op_sel_hi:[1,0]
	v_pk_mul_f32 v[36:37], v[36:37], v[50:51] op_sel_hi:[1,0]
	v_max_f32_e32 v34, 0, v34
	v_cvt_pk_bf16_f32 v45, v48, v45
	global_store_dwordx4 v[46:47], v[42:45], off
	v_pk_mul_f32 v[40:41], v[40:41], v[50:51] op_sel_hi:[1,0]
	v_max_f32_e32 v35, 0, v35
	v_mul_f32_e32 v42, v34, v34
	v_max_f32_e32 v34, 0, v39
	v_max_f32_e32 v36, 0, v36
	v_max_f32_e32 v38, 0, v38
	v_mul_f32_e32 v34, v34, v34
	v_mul_f32_e32 v39, v35, v35
	v_max_f32_e32 v35, 0, v40
	v_mul_f32_e32 v40, v36, v36
	v_max_f32_e32 v36, 0, v41
	v_max_f32_e32 v37, 0, v37
	v_mul_f32_e32 v38, v38, v38
	v_mul_f32_e32 v35, v35, v35
	v_mul_f32_e32 v36, v36, v36
	v_mul_f32_e32 v37, v37, v37
	v_cvt_pk_bf16_f32 v34, v38, v34
	v_cvt_pk_bf16_f32 v35, v35, v36
	v_cvt_pk_bf16_f32 v36, v42, v39
	v_cvt_pk_bf16_f32 v37, v40, v37
	global_store_dwordx4 v[52:53], v[34:37], off offset:256
	s_mov_b32 s2, 0x280000
	s_nop 0
	v_fmamk_f32 v34, v253, 0x3a000000, v207
	v_rsq_f32_e32 v34, v34
	v_lshl_add_u64 v[36:37], v[152:153], 0, s[4:5]
	s_mov_b64 s[4:5], 0x2c0000
	v_pk_mul_f32 v[26:27], v[26:27], v[34:35] op_sel_hi:[1,0]
	v_pk_mul_f32 v[30:31], v[30:31], v[34:35] op_sel_hi:[1,0]
	v_pk_mul_f32 v[28:29], v[28:29], v[34:35] op_sel_hi:[1,0]
	v_max_f32_e32 v26, 0, v26
	v_pk_mul_f32 v[32:33], v[32:33], v[34:35] op_sel_hi:[1,0]
	v_max_f32_e32 v30, 0, v30
	v_mul_f32_e32 v35, v26, v26
	v_max_f32_e32 v26, 0, v31
	v_max_f32_e32 v27, 0, v27
	v_max_f32_e32 v28, 0, v28
	v_mul_f32_e32 v30, v30, v30
	v_mul_f32_e32 v26, v26, v26
	v_mul_f32_e32 v31, v27, v27
	v_max_f32_e32 v27, 0, v32
	v_mul_f32_e32 v32, v28, v28
	v_max_f32_e32 v28, 0, v33
	v_mul_f32_e32 v27, v27, v27
	v_mul_f32_e32 v28, v28, v28
	v_max_f32_e32 v29, 0, v29
	v_cvt_pk_bf16_f32 v26, v30, v26
	v_add_co_u32_e32 v30, vcc, s2, v152
	v_pk_mul_f32 v[18:19], v[18:19], v[34:35] op_sel_hi:[1,0]
	v_mul_f32_e32 v29, v29, v29
	v_cvt_pk_bf16_f32 v27, v27, v28
	v_cvt_pk_bf16_f32 v28, v35, v31
	v_addc_co_u32_e32 v31, vcc, 0, v153, vcc
	v_pk_mul_f32 v[22:23], v[22:23], v[34:35] op_sel_hi:[1,0]
	v_pk_mul_f32 v[20:21], v[20:21], v[34:35] op_sel_hi:[1,0]
	v_max_f32_e32 v18, 0, v18
	v_cvt_pk_bf16_f32 v29, v32, v29
	global_store_dwordx4 v[30:31], v[26:29], off
	v_pk_mul_f32 v[24:25], v[24:25], v[34:35] op_sel_hi:[1,0]
	v_max_f32_e32 v19, 0, v19
	v_mul_f32_e32 v26, v18, v18
	v_max_f32_e32 v18, 0, v23
	v_max_f32_e32 v20, 0, v20
	v_max_f32_e32 v22, 0, v22
	v_mul_f32_e32 v18, v18, v18
	v_mul_f32_e32 v23, v19, v19
	v_max_f32_e32 v19, 0, v24
	v_mul_f32_e32 v24, v20, v20
	v_max_f32_e32 v20, 0, v25
	v_max_f32_e32 v21, 0, v21
	v_mul_f32_e32 v22, v22, v22
	v_mul_f32_e32 v19, v19, v19
	v_mul_f32_e32 v20, v20, v20
	v_mul_f32_e32 v21, v21, v21
	v_cvt_pk_bf16_f32 v18, v22, v18
	v_cvt_pk_bf16_f32 v19, v19, v20
	v_cvt_pk_bf16_f32 v20, v26, v23
	v_cvt_pk_bf16_f32 v21, v24, v21
	global_store_dwordx4 v[36:37], v[18:21], off offset:256
	s_mov_b32 s2, 0x2c0000
	s_nop 0
	v_fmamk_f32 v18, v254, 0x3a000000, v207
	v_rsq_f32_e32 v18, v18
	v_lshl_add_u64 v[20:21], v[152:153], 0, s[4:5]
	v_pk_mul_f32 v[10:11], v[10:11], v[18:19] op_sel_hi:[1,0]
	v_pk_mul_f32 v[14:15], v[14:15], v[18:19] op_sel_hi:[1,0]
	v_pk_mul_f32 v[12:13], v[12:13], v[18:19] op_sel_hi:[1,0]
	v_max_f32_e32 v10, 0, v10
	v_pk_mul_f32 v[16:17], v[16:17], v[18:19] op_sel_hi:[1,0]
	v_max_f32_e32 v14, 0, v14
	v_mul_f32_e32 v19, v10, v10
	v_max_f32_e32 v10, 0, v15
	v_max_f32_e32 v11, 0, v11
	v_max_f32_e32 v12, 0, v12
	v_mul_f32_e32 v14, v14, v14
	v_mul_f32_e32 v10, v10, v10
	v_mul_f32_e32 v15, v11, v11
	v_max_f32_e32 v11, 0, v16
	v_mul_f32_e32 v16, v12, v12
	v_max_f32_e32 v12, 0, v17
	v_mul_f32_e32 v11, v11, v11
	v_mul_f32_e32 v12, v12, v12
	v_max_f32_e32 v13, 0, v13
	v_cvt_pk_bf16_f32 v10, v14, v10
	v_add_co_u32_e32 v14, vcc, s2, v152
	v_pk_mul_f32 v[4:5], v[4:5], v[18:19] op_sel_hi:[1,0]
	v_pk_mul_f32 v[2:3], v[2:3], v[18:19] op_sel_hi:[1,0]
	v_mul_f32_e32 v13, v13, v13
	v_cvt_pk_bf16_f32 v11, v11, v12
	v_cvt_pk_bf16_f32 v12, v19, v15
	v_addc_co_u32_e32 v15, vcc, 0, v153, vcc
	v_pk_mul_f32 v[8:9], v[8:9], v[18:19] op_sel_hi:[1,0]
	v_pk_mul_f32 v[6:7], v[6:7], v[18:19] op_sel_hi:[1,0]
	v_max_f32_e32 v2, 0, v2
	v_max_f32_e32 v3, 0, v3
	v_max_f32_e32 v4, 0, v4
	v_cvt_pk_bf16_f32 v13, v16, v13
	global_store_dwordx4 v[14:15], v[10:13], off
	v_max_f32_e32 v5, 0, v5
	v_max_f32_e32 v6, 0, v6
	v_mul_f32_e32 v10, v2, v2
	v_max_f32_e32 v2, 0, v7
	v_mul_f32_e32 v7, v3, v3
	v_max_f32_e32 v3, 0, v8
	v_mul_f32_e32 v8, v4, v4
	v_max_f32_e32 v4, 0, v9
	v_mul_f32_e32 v2, v2, v2
	v_mul_f32_e32 v3, v3, v3
	v_mul_f32_e32 v4, v4, v4
	v_mul_f32_e32 v5, v5, v5
	s_andn2_b64 vcc, exec, s[42:43]
	v_mul_f32_e32 v6, v6, v6
	v_cvt_pk_bf16_f32 v2, v6, v2
	v_cvt_pk_bf16_f32 v3, v3, v4
	v_cvt_pk_bf16_f32 v4, v10, v7
	v_cvt_pk_bf16_f32 v5, v8, v5
	global_store_dwordx4 v[20:21], v[2:5], off offset:256
	s_cbranch_vccnz .LBB0_678
	s_andn2_b64 vcc, exec, s[44:45]
	s_cbranch_vccnz .LBB0_677
	s_barrier
	s_branch .LBB0_677

; __global__ void __launch_bounds__(512, 2) mega_fwd(Args args) {
	.amdhsa_kernel _Z8mega_fwd4Args
		.amdhsa_group_segment_fixed_size 0
		.amdhsa_private_segment_fixed_size 0
		.amdhsa_kernarg_size 392
		.amdhsa_user_sgpr_count 2
		.amdhsa_user_sgpr_dispatch_ptr 0
		.amdhsa_user_sgpr_queue_ptr 0
		.amdhsa_user_sgpr_kernarg_segment_ptr 1
		.amdhsa_user_sgpr_dispatch_id 0
		.amdhsa_user_sgpr_kernarg_preload_length 0
		.amdhsa_user_sgpr_kernarg_preload_offset 0
		.amdhsa_user_sgpr_private_segment_size 0
		.amdhsa_uses_dynamic_stack 0
		.amdhsa_enable_private_segment 0
		.amdhsa_system_sgpr_workgroup_id_x 1
		.amdhsa_system_sgpr_workgroup_id_y 0
		.amdhsa_system_sgpr_workgroup_id_z 0
		.amdhsa_system_sgpr_workgroup_info 0
		.amdhsa_system_vgpr_workitem_id 2
		.amdhsa_next_free_vgpr 256
		.amdhsa_next_free_sgpr 100
		.amdhsa_accum_offset 256
		.amdhsa_reserve_vcc 1
		.amdhsa_float_round_mode_32 0
		.amdhsa_float_round_mode_16_64 0
		.amdhsa_float_denorm_mode_32 3
		.amdhsa_float_denorm_mode_16_64 3
		.amdhsa_dx10_clamp 1
		.amdhsa_ieee_mode 1
		.amdhsa_fp16_overflow 0
		.amdhsa_tg_split 0
		.amdhsa_exception_fp_ieee_invalid_op 0
		.amdhsa_exception_fp_denorm_src 0
		.amdhsa_exception_fp_ieee_div_zero 0
		.amdhsa_exception_fp_ieee_overflow 0
		.amdhsa_exception_fp_ieee_underflow 0
		.amdhsa_exception_fp_ieee_inexact 0
		.amdhsa_exception_int_div_zero 0
	.end_amdhsa_kernel

; __global__ void __launch_bounds__(512, 2) mega_fwd(Args args) {
amdhsa.kernels:
  - .agpr_count:     0
    .args:
      - .offset:         0
        .size:           136
        .value_kind:     by_value
      - .offset:         136
        .size:           4
        .value_kind:     hidden_block_count_x
      - .offset:         140
        .size:           4
        .value_kind:     hidden_block_count_y
      - .offset:         144
        .size:           4
        .value_kind:     hidden_block_count_z
      - .offset:         148
        .size:           2
        .value_kind:     hidden_group_size_x
      - .offset:         150
        .size:           2
        .value_kind:     hidden_group_size_y
      - .offset:         152
        .size:           2
        .value_kind:     hidden_group_size_z
      - .offset:         154
        .size:           2
        .value_kind:     hidden_remainder_x
      - .offset:         156
        .size:           2
        .value_kind:     hidden_remainder_y
      - .offset:         158
        .size:           2
        .value_kind:     hidden_remainder_z
      - .offset:         176
        .size:           8
        .value_kind:     hidden_global_offset_x
      - .offset:         184
        .size:           8
        .value_kind:     hidden_global_offset_y
      - .offset:         192
        .size:           8
        .value_kind:     hidden_global_offset_z
      - .offset:         200
        .size:           2
        .value_kind:     hidden_grid_dims
      - .offset:         224
        .size:           8
        .value_kind:     hidden_multigrid_sync_arg
      - .offset:         256
        .size:           4
        .value_kind:     hidden_dynamic_lds_size
    .group_segment_fixed_size: 0
    .kernarg_segment_align: 8
    .kernarg_segment_size: 392
    .language:       OpenCL C
    .language_version:
      - 2
      - 0
    .max_flat_workgroup_size: 512
    .name:           _Z8mega_fwd4Args
    .private_segment_fixed_size: 0
    .sgpr_count:     106
    .sgpr_spill_count: 182
    .symbol:         _Z8mega_fwd4Args.kd
    .uniform_work_group_size: 1
    .uses_dynamic_stack: false
    .vgpr_count:     256
    .vgpr_spill_count: 0
    .wavefront_size: 64
